# out-proj epilogue: accumulators and row/column terms exchanged between lanes (same as FF2) so four consecutive lanes access 64 contiguous bytes of one row
# baseline (speedup 1.0000x reference)
; #define PG8_STAGE(bufoff, gbase, voff) do { _Pragma("unroll") for (int _i = 0; _i < 2; ++_i) \
;     __builtin_amdgcn_global_load_lds((const unsigned*)((const char*)(gbase) + (voff)[_i]), (LAS unsigned*)(lds + (bufoff) + ldsw + _i * 8192), 16, 0, 0); } while (0)
; #define PG8_WAIT_V(n) asm volatile("s_waitcnt vmcnt(" #n ")" ::: "memory")
; #define PG8_BAR __builtin_amdgcn_s_barrier()
; template <class Epi>
; __device__ __forceinline__ void gemm_phase(LAS unsigned char* lds, const Gemm g, const StaticOrder& S, const Epi& E) {
;     ...
;   PG8_STAGE(PG8_SB(0, 0), cB, voffB); PG8_STAGE(PG8_SA(0, 0), cA, voffA); PG8_STAGE(PG8_SB(0, 1), cB + hstepB, voffB); PG8_STAGE(PG8_SA(0, 1), cA + hstepA, voffA);
;   if (wr == 1) PG8_BAR;
;   PG8_WAIT_V(4); PG8_BAR;
;   PG8_STAGE(PG8_SB(1, 0), cB + kstep, voffB); PG8_STAGE(PG8_SA(1, 0), cA + kstep, voffA); PG8_STAGE(PG8_SB(1, 1), cB + hstepB + kstep, voffB);
;   PG8_WAIT_V(6); PG8_BAR;
;   __device__ __forceinline__ void operator()(const f32x4 (&acc)[2][2][4][2], const Unit& u, int wr, int wc, int fr, int fq) const {
;     ...
;       float* pbase = part + (size_t)(u.kt0 / u.nt) * MS * 1024;
; #pragma unroll
;       for (int ai = 0; ai < 2; ++ai)
; #pragma unroll
;         for (int m = 0; m < 4; ++m) {
;           float* orow = pbase + (size_t)(u.pm * 256 + ai * 128 + wr * 64 + m * 16 + fr - MP) * 1024;
; #pragma unroll
;           for (int bj = 0; bj < 2; ++bj)
; #pragma unroll
;             for (int n = 0; n < 2; ++n) *(f32x4*)(orow + u.pn * 256 + bj * 128 + wc * 32 + 16 * n + 4 * fq) = acc[ai][bj][m][n];
.LBB0_3639:
	s_lshl_b32 s8, s2, 6
	s_lshl_b32 s9, s2, 13
	s_lshl_b32 s2, s3, 5
	s_and_b32 s42, s2, 0x60
	s_add_i32 m0, s38, 0x18000
	v_lshl_add_u64 v[6:7], v[6:7], 0, s[16:17]
	s_lshl_b32 s10, s42, 7
	s_waitcnt vmcnt(4)
	s_barrier
	global_load_lds_dwordx4 v[6:7], off
	v_lshl_add_u64 v[4:5], v[4:5], 0, s[16:17]
	s_add_i32 m0, s38, 0x1a000
	s_add_i32 s43, s38, 0x8000
	s_add_i32 s44, s38, 0xa000
	global_load_lds_dwordx4 v[4:5], off
	v_lshl_add_u64 v[2:3], v[2:3], 0, s[16:17]
	s_mov_b32 m0, s43
	s_add_u32 s2, s26, 0x40080
	global_load_lds_dwordx4 v[2:3], off
	v_lshl_add_u64 v[0:1], v[0:1], 0, s[16:17]
	s_mov_b32 m0, s44
	s_addc_u32 s3, s27, 0
	global_load_lds_dwordx4 v[0:1], off
	s_add_i32 m0, s38, 0x1c000
	v_lshl_add_u64 v[0:1], s[2:3], 0, v[134:135]
	global_load_lds_dwordx4 v[0:1], off
	v_lshl_add_u64 v[0:1], s[2:3], 0, v[136:137]
	s_add_i32 m0, s38, 0x1e000
	s_lshl_b32 s2, s42, 2
	global_load_lds_dwordx4 v[0:1], off
	v_and_b32_e32 v0, 15, v8
	v_or_b32_e32 v139, s8, v0
	s_addk_i32 s8, 0x8000
	s_add_u32 s3, s6, s2
	v_or_b32_e32 v187, s8, v0
	s_addc_u32 s8, s7, 0
	s_add_u32 s45, s3, 0x1e482000
	s_addc_u32 s46, s8, 0
	v_bfe_u32 v1, v8, 4, 2
	s_add_u32 s2, s0, s2
	v_lshlrev_b32_e32 v16, 4, v1
	s_addc_u32 s3, s1, 0
	v_lshl_add_u64 v[140:141], s[2:3], 0, v[16:17]
	s_lshl_b32 s2, s42, 1
	s_add_u32 s2, s6, s2
	v_lshl_or_b32 v2, v0, 6, v16
	s_addc_u32 s3, s7, 0
	v_lshlrev_b32_e32 v16, 3, v1
	v_lshlrev_b32_e32 v138, 2, v1
	v_lshl_add_u64 v[0:1], s[2:3], 0, v[16:17]
	s_mov_b64 s[2:3], 0x39c0000
	v_lshl_add_u64 v[142:143], v[0:1], 0, s[2:3]
	v_lshlrev_b32_e32 v0, 14, v9
	v_and_b32_e32 v0, 0xffff8000, v0
	v_lshl_add_u32 v0, v10, 11, v0
	v_and_b32_e32 v1, 1, v9
	v_lshl_or_b32 v0, v1, 6, v0
	v_lshl_add_u32 v144, v11, 1, v0
	v_lshlrev_b32_e32 v0, 14, v12
	v_lshlrev_b32_e32 v3, 2, v8
	v_and_b32_e32 v0, 0xffff8000, v0
	v_and_b32_e32 v3, 32, v3
	s_waitcnt vmcnt(6)
	v_lshl_add_u32 v0, v13, 11, v0
	v_and_b32_e32 v1, 1, v12
	v_bitop3_b32 v4, v2, s9, v3 bitop3:0xde
	s_cmp_lg_u64 s[0:1], 0
	v_lshl_or_b32 v0, v1, 6, v0
	v_bitop3_b32 v186, v2, s10, v3 bitop3:0xde
	v_or_b32_e32 v188, 16, v187
	v_or_b32_e32 v189, 32, v187
	v_or_b32_e32 v190, 48, v187
	v_or_b32_e32 v191, 16, v139
	v_or_b32_e32 v192, 32, v139
	v_or_b32_e32 v193, 48, v139
	v_add_u32_e32 v194, 0x80, v139
	v_add_u32_e32 v195, 0x90, v139
	v_add_u32_e32 v196, 0xa0, v139
	v_add_u32_e32 v197, 0xb0, v139
	v_and_b32_e32 v200, 3, v252
	v_lshlrev_b32_e32 v200, 4, v200
	v_and_b32_e32 v201, 12, v252
	v_bfe_u32 v202, v252, 4, 2
	v_or3_b32 v200, v200, v201, v202
	v_lshlrev_b32_e32 v200, 2, v200
	ds_bpermute_b32 v138, v200, v138
	ds_bpermute_b32 v139, v200, v139
	ds_bpermute_b32 v140, v200, v140
	ds_bpermute_b32 v141, v200, v141
	ds_bpermute_b32 v142, v200, v142
	ds_bpermute_b32 v143, v200, v143
	ds_bpermute_b32 v187, v200, v187
	ds_bpermute_b32 v188, v200, v188
	ds_bpermute_b32 v189, v200, v189
	ds_bpermute_b32 v190, v200, v190
	ds_bpermute_b32 v191, v200, v191
	ds_bpermute_b32 v192, v200, v192
	s_waitcnt lgkmcnt(0)
	ds_bpermute_b32 v193, v200, v193
	ds_bpermute_b32 v194, v200, v194
	ds_bpermute_b32 v195, v200, v195
	ds_bpermute_b32 v196, v200, v196
	ds_bpermute_b32 v197, v200, v197
	s_waitcnt lgkmcnt(0)
	s_cselect_b64 s[2:3], -1, 0
	v_mov_b32_e32 v145, v17
	v_lshl_add_u32 v146, v14, 1, v0
	v_mov_b32_e32 v147, v17
	s_mov_b32 s47, 0
	v_add_u32_e32 v198, 0, v4
	s_barrier
	s_branch .LBB0_3643

; #define PG8_STAGE(bufoff, gbase, voff) do { _Pragma("unroll") for (int _i = 0; _i < 2; ++_i) \
;     __builtin_amdgcn_global_load_lds((const unsigned*)((const char*)(gbase) + (voff)[_i]), (LAS unsigned*)(lds + (bufoff) + ldsw + _i * 8192), 16, 0, 0); } while (0)
; #define PG8_LDA(dst, b, h) do { _Pragma("unroll") for (int m = 0; m < 4; ++m) _Pragma("unroll") for (int k = 0; k < 2; ++k) dst[m][k] = *(const LAS bf16x8*)(lds + PG8_SA(b, h) + aoff + m * 2048 + k * 1024); } while (0)
; #define PG8_LDB(dst, b, h) do { _Pragma("unroll") for (int n = 0; n < 2; ++n) _Pragma("unroll") for (int k = 0; k < 2; ++k) dst[n][k] = *(const LAS bf16x8*)(lds + PG8_SB(b, h) + boff + n * 2048 + k * 1024); } while (0)
; #define PG8_MMA(ai, bj, At, Bt) do { __builtin_amdgcn_s_setprio(1); _Pragma("unroll") for (int m = 0; m < 4; ++m) _Pragma("unroll") for (int n = 0; n < 2; ++n) _Pragma("unroll") for (int k = 0; k < 2; ++k) \
;     acc[ai][bj][m][n] = __builtin_amdgcn_mfma_f32_16x16x32_bf16(Bt[n][k], At[m][k], acc[ai][bj][m][n], 0, 0, 0); __builtin_amdgcn_s_setprio(0); } while (0)
; #define PG8_WAIT_V(n) asm volatile("s_waitcnt vmcnt(" #n ")" ::: "memory")
; #define PG8_WAIT_L(n) asm volatile("s_waitcnt lgkmcnt(" #n ")" ::: "memory")
; #define PG8_BAR __builtin_amdgcn_s_barrier()
; #define PG8_SCHED __builtin_amdgcn_sched_barrier(0)
; template <class Epi>
; __device__ __forceinline__ void gemm_phase(LAS unsigned char* lds, const Gemm g, const StaticOrder& S, const Epi& E) {
;     ...
;       PG8_LDB(B0, 0, 0); PG8_SCHED; PG8_LDA(At, 0, 0); PG8_STAGE(PG8_SA(1, 1), a1 + hstepA, voffA);
;       PG8_WAIT_L(8); PG8_BAR; PG8_WAIT_L(0); PG8_MMA(0, 0, At, B0); PG8_BAR; PG8_SCHED;
;       PG8_LDB(B1, 0, 1); PG8_STAGE(PG8_SB(0, 0), b2, voffB);
;       PG8_BAR; PG8_WAIT_L(0); PG8_MMA(0, 1, At, B1); PG8_BAR;
;       PG8_LDA(At, 0, 1); PG8_STAGE(PG8_SA(0, 0), a2, voffA);
;       PG8_BAR; PG8_WAIT_L(0); PG8_MMA(1, 0, At, B0); PG8_BAR; PG8_SCHED;
;       PG8_STAGE(PG8_SB(0, 1), b2 + hstepB, voffB);
;       PG8_WAIT_V(6); PG8_BAR; PG8_MMA(1, 1, At, B1); PG8_BAR;
.LBB0_3657:
	s_add_u32 s21, s24, 0xfffc0080
	s_addc_u32 s23, s25, -1
	s_add_i32 s53, 0, 0x10000
	v_add_u32_e32 v16, s53, v186
	ds_read_b128 v[130:133], v16
	ds_read_b128 v[148:151], v16 offset:1024
	ds_read_b128 v[152:155], v16 offset:2048
	ds_read_b128 v[156:159], v16 offset:3072
	s_cmp_eq_u32 s50, s11
	s_cselect_b32 s29, s15, s23
	s_cselect_b32 s28, s14, s21
	s_cselect_b32 s27, s1, s9
	s_cselect_b32 s26, s0, s7
	v_lshl_add_u64 v[184:185], s[24:25], 0, v[144:145]
	s_add_i32 m0, s38, 0xc000
	ds_read_b128 v[160:163], v198
	ds_read_b128 v[164:167], v198 offset:1024
	ds_read_b128 v[168:171], v198 offset:2048
	ds_read_b128 v[172:175], v198 offset:3072
	ds_read_b128 v[176:179], v198 offset:4096
	ds_read_b128 v[180:183], v198 offset:5120
	ds_read_b128 v[200:203], v198 offset:6144
	ds_read_b128 v[204:207], v198 offset:7168
	global_load_lds_dwordx4 v[184:185], off
	v_lshl_add_u64 v[184:185], s[24:25], 0, v[146:147]
	s_add_i32 m0, s38, 0xe000
	s_nop 0
	global_load_lds_dwordx4 v[184:185], off
	s_waitcnt lgkmcnt(8)
	s_barrier
	s_waitcnt lgkmcnt(0)
	s_setprio 1
	s_waitcnt lgkmcnt(0)
	v_mfma_f32_16x16x32_bf16 v[126:129], v[130:133], v[160:163], v[126:129]
	v_mfma_f32_16x16x32_bf16 v[122:125], v[152:155], v[160:163], v[122:125]
	v_mfma_f32_16x16x32_bf16 v[118:121], v[130:133], v[168:171], v[118:121]
	v_mfma_f32_16x16x32_bf16 v[106:109], v[152:155], v[168:171], v[106:109]
	v_mfma_f32_16x16x32_bf16 v[98:101], v[130:133], v[176:179], v[98:101]
	v_mfma_f32_16x16x32_bf16 v[90:93], v[152:155], v[176:179], v[90:93]
	v_mfma_f32_16x16x32_bf16 v[82:85], v[130:133], v[200:203], v[82:85]
	v_mfma_f32_16x16x32_bf16 v[74:77], v[152:155], v[200:203], v[74:77]
	v_mfma_f32_16x16x32_bf16 v[126:129], v[148:151], v[164:167], v[126:129]
	v_mfma_f32_16x16x32_bf16 v[122:125], v[156:159], v[164:167], v[122:125]
	v_mfma_f32_16x16x32_bf16 v[118:121], v[148:151], v[172:175], v[118:121]
	v_mfma_f32_16x16x32_bf16 v[106:109], v[156:159], v[172:175], v[106:109]
	v_mfma_f32_16x16x32_bf16 v[98:101], v[148:151], v[180:183], v[98:101]
	v_mfma_f32_16x16x32_bf16 v[90:93], v[156:159], v[180:183], v[90:93]
	v_mfma_f32_16x16x32_bf16 v[82:85], v[148:151], v[204:207], v[82:85]
	v_mfma_f32_16x16x32_bf16 v[74:77], v[156:159], v[204:207], v[74:77]
	s_setprio 0
	s_barrier
	s_add_i32 s21, 0, 0x14000
	s_add_i32 s23, s53, s31
	v_add_u32_e32 v16, s21, v186
	v_lshl_add_u64 v[184:185], s[26:27], 0, v[134:135]
	s_mov_b32 m0, s23
	ds_read_b128 v[208:211], v16
	ds_read_b128 v[212:215], v16 offset:1024
	ds_read_b128 v[216:219], v16 offset:2048
	ds_read_b128 v[220:223], v16 offset:3072
	global_load_lds_dwordx4 v[184:185], off
	v_lshl_add_u64 v[224:225], s[26:27], 0, v[136:137]
	s_add_i32 m0, s23, 0x2000
	s_nop 0
	global_load_lds_dwordx4 v[224:225], off
	s_barrier
	s_waitcnt lgkmcnt(0)
	s_setprio 1
	s_waitcnt lgkmcnt(0)
	v_mfma_f32_16x16x32_bf16 v[114:117], v[208:211], v[160:163], v[114:117]
	v_mfma_f32_16x16x32_bf16 v[110:113], v[216:219], v[160:163], v[110:113]
	v_mfma_f32_16x16x32_bf16 v[102:105], v[208:211], v[168:171], v[102:105]
	v_mfma_f32_16x16x32_bf16 v[94:97], v[216:219], v[168:171], v[94:97]
	v_mfma_f32_16x16x32_bf16 v[86:89], v[208:211], v[176:179], v[86:89]
	v_mfma_f32_16x16x32_bf16 v[78:81], v[216:219], v[176:179], v[78:81]
	v_mfma_f32_16x16x32_bf16 v[70:73], v[208:211], v[200:203], v[70:73]
	v_mfma_f32_16x16x32_bf16 v[66:69], v[216:219], v[200:203], v[66:69]
	v_mfma_f32_16x16x32_bf16 v[114:117], v[212:215], v[164:167], v[114:117]
	v_mfma_f32_16x16x32_bf16 v[110:113], v[220:223], v[164:167], v[110:113]
	v_mfma_f32_16x16x32_bf16 v[102:105], v[212:215], v[172:175], v[102:105]
	v_mfma_f32_16x16x32_bf16 v[94:97], v[220:223], v[172:175], v[94:97]
	v_mfma_f32_16x16x32_bf16 v[86:89], v[212:215], v[180:183], v[86:89]
	v_mfma_f32_16x16x32_bf16 v[78:81], v[220:223], v[180:183], v[78:81]
	v_mfma_f32_16x16x32_bf16 v[70:73], v[212:215], v[204:207], v[70:73]
	v_mfma_f32_16x16x32_bf16 v[66:69], v[220:223], v[204:207], v[66:69]
	s_setprio 0
	s_mov_b32 m0, s38
	v_lshl_add_u64 v[226:227], s[28:29], 0, v[134:135]
	s_barrier
	ds_read_b128 v[160:163], v198 offset:16384
	ds_read_b128 v[164:167], v198 offset:17408
	ds_read_b128 v[168:171], v198 offset:18432
	ds_read_b128 v[172:175], v198 offset:19456
	ds_read_b128 v[176:179], v198 offset:20480
	ds_read_b128 v[180:183], v198 offset:21504
	ds_read_b128 v[200:203], v198 offset:22528
	ds_read_b128 v[204:207], v198 offset:23552
	global_load_lds_dwordx4 v[226:227], off
	v_lshl_add_u64 v[228:229], s[28:29], 0, v[136:137]
	s_mov_b32 m0, s39
	s_nop 0
	global_load_lds_dwordx4 v[228:229], off
	s_barrier
	s_waitcnt lgkmcnt(0)
	s_setprio 1
	s_waitcnt lgkmcnt(0)
	v_mfma_f32_16x16x32_bf16 v[62:65], v[130:133], v[160:163], v[62:65]
	v_mfma_f32_16x16x32_bf16 v[58:61], v[152:155], v[160:163], v[58:61]
	v_mfma_f32_16x16x32_bf16 v[50:53], v[130:133], v[168:171], v[50:53]
	v_mfma_f32_16x16x32_bf16 v[42:45], v[152:155], v[168:171], v[42:45]
	v_mfma_f32_16x16x32_bf16 v[34:37], v[130:133], v[176:179], v[34:37]
	v_mfma_f32_16x16x32_bf16 v[26:29], v[152:155], v[176:179], v[26:29]
	v_mfma_f32_16x16x32_bf16 v[18:21], v[130:133], v[200:203], v[18:21]
	v_mfma_f32_16x16x32_bf16 v[8:11], v[152:155], v[200:203], v[8:11]
	v_mfma_f32_16x16x32_bf16 v[62:65], v[148:151], v[164:167], v[62:65]
	v_mfma_f32_16x16x32_bf16 v[58:61], v[156:159], v[164:167], v[58:61]
	v_mfma_f32_16x16x32_bf16 v[50:53], v[148:151], v[172:175], v[50:53]
	v_mfma_f32_16x16x32_bf16 v[42:45], v[156:159], v[172:175], v[42:45]
	v_mfma_f32_16x16x32_bf16 v[34:37], v[148:151], v[180:183], v[34:37]
	v_mfma_f32_16x16x32_bf16 v[26:29], v[156:159], v[180:183], v[26:29]
	v_mfma_f32_16x16x32_bf16 v[18:21], v[148:151], v[204:207], v[18:21]
	v_mfma_f32_16x16x32_bf16 v[8:11], v[156:159], v[204:207], v[8:11]
	s_setprio 0
	s_barrier
; #define PG8_STAGE(bufoff, gbase, voff) do { _Pragma("unroll") for (int _i = 0; _i < 2; ++_i) \
;     __builtin_amdgcn_global_load_lds((const unsigned*)((const char*)(gbase) + (voff)[_i]), (LAS unsigned*)(lds + (bufoff) + ldsw + _i * 8192), 16, 0, 0); } while (0)
; #define PG8_LDA(dst, b, h) do { _Pragma("unroll") for (int m = 0; m < 4; ++m) _Pragma("unroll") for (int k = 0; k < 2; ++k) dst[m][k] = *(const LAS bf16x8*)(lds + PG8_SA(b, h) + aoff + m * 2048 + k * 1024); } while (0)
; #define PG8_LDB(dst, b, h) do { _Pragma("unroll") for (int n = 0; n < 2; ++n) _Pragma("unroll") for (int k = 0; k < 2; ++k) dst[n][k] = *(const LAS bf16x8*)(lds + PG8_SB(b, h) + boff + n * 2048 + k * 1024); } while (0)
; #define PG8_MMA(ai, bj, At, Bt) do { __builtin_amdgcn_s_setprio(1); _Pragma("unroll") for (int m = 0; m < 4; ++m) _Pragma("unroll") for (int n = 0; n < 2; ++n) _Pragma("unroll") for (int k = 0; k < 2; ++k) \
;     acc[ai][bj][m][n] = __builtin_amdgcn_mfma_f32_16x16x32_bf16(Bt[n][k], At[m][k], acc[ai][bj][m][n], 0, 0, 0); __builtin_amdgcn_s_setprio(0); } while (0)
; #define PG8_WAIT_V(n) asm volatile("s_waitcnt vmcnt(" #n ")" ::: "memory")
; #define PG8_WAIT_L(n) asm volatile("s_waitcnt lgkmcnt(" #n ")" ::: "memory")
; #define PG8_BAR __builtin_amdgcn_s_barrier()
; #define PG8_SCHED __builtin_amdgcn_sched_barrier(0)
; template <class Epi>
; __device__ __forceinline__ void gemm_phase(LAS unsigned char* lds, const Gemm g, const StaticOrder& S, const Epi& E) {
;     ...
;       PG8_STAGE(PG8_SB(0, 1), b2 + hstepB, voffB);
;       PG8_WAIT_V(6); PG8_BAR; PG8_MMA(1, 1, At, B1); PG8_BAR;
;       PG8_LDB(B0, 1, 0); PG8_SCHED; PG8_LDA(At, 1, 0); PG8_STAGE(PG8_SA(0, 1), a2 + hstepA, voffA);
;       PG8_WAIT_L(8); PG8_BAR; PG8_WAIT_L(0); PG8_MMA(0, 0, At, B0); PG8_BAR; PG8_SCHED;
;       PG8_LDB(B1, 1, 1); PG8_STAGE(PG8_SB(1, 0), b3, voffB);
;       PG8_BAR; PG8_WAIT_L(0); PG8_MMA(0, 1, At, B1); PG8_BAR;
;       PG8_LDA(At, 1, 1); PG8_STAGE(PG8_SA(1, 0), a3, voffA);
	s_add_u32 s54, s26, 0x40000
	s_addc_u32 s55, s27, 0
	s_add_i32 s21, s21, s31
	v_lshl_add_u64 v[130:131], s[54:55], 0, v[134:135]
	s_mov_b32 m0, s21
	s_nop 0
	global_load_lds_dwordx4 v[130:131], off
	v_lshl_add_u64 v[130:131], s[54:55], 0, v[136:137]
	s_add_i32 m0, s21, 0x2000
	s_nop 0
	global_load_lds_dwordx4 v[130:131], off
	s_waitcnt vmcnt(6)
	s_barrier
	s_setprio 1
	v_mfma_f32_16x16x32_bf16 v[54:57], v[208:211], v[160:163], v[54:57]
	v_mfma_f32_16x16x32_bf16 v[46:49], v[216:219], v[160:163], v[46:49]
	v_mfma_f32_16x16x32_bf16 v[38:41], v[208:211], v[168:171], v[38:41]
	v_mfma_f32_16x16x32_bf16 v[30:33], v[216:219], v[168:171], v[30:33]
	v_mfma_f32_16x16x32_bf16 v[22:25], v[208:211], v[176:179], v[22:25]
	v_mfma_f32_16x16x32_bf16 v[12:15], v[216:219], v[176:179], v[12:15]
	v_mfma_f32_16x16x32_bf16 v[4:7], v[208:211], v[200:203], v[4:7]
	v_mfma_f32_16x16x32_bf16 v[0:3], v[216:219], v[200:203], v[0:3]
	v_mfma_f32_16x16x32_bf16 v[54:57], v[212:215], v[164:167], v[54:57]
	v_mfma_f32_16x16x32_bf16 v[46:49], v[220:223], v[164:167], v[46:49]
	v_mfma_f32_16x16x32_bf16 v[38:41], v[212:215], v[172:175], v[38:41]
	v_mfma_f32_16x16x32_bf16 v[30:33], v[220:223], v[172:175], v[30:33]
	v_mfma_f32_16x16x32_bf16 v[22:25], v[212:215], v[180:183], v[22:25]
	v_mfma_f32_16x16x32_bf16 v[12:15], v[220:223], v[180:183], v[12:15]
	v_mfma_f32_16x16x32_bf16 v[4:7], v[212:215], v[204:207], v[4:7]
	v_mfma_f32_16x16x32_bf16 v[0:3], v[220:223], v[204:207], v[0:3]
	s_setprio 0
	s_add_i32 s21, 0, 0x18000
	v_add_u32_e32 v16, s21, v186
	s_barrier
	ds_read_b128 v[130:133], v16
	ds_read_b128 v[148:151], v16 offset:1024
	ds_read_b128 v[152:155], v16 offset:2048
	ds_read_b128 v[156:159], v16 offset:3072
	s_add_u32 s28, s28, 0x40000
	s_addc_u32 s29, s29, 0
	s_mov_b32 m0, s40
	v_lshl_add_u64 v[208:209], s[28:29], 0, v[134:135]
	ds_read_b128 v[160:163], v198 offset:32768
	ds_read_b128 v[164:167], v198 offset:33792
	ds_read_b128 v[168:171], v198 offset:34816
	ds_read_b128 v[172:175], v198 offset:35840
	ds_read_b128 v[176:179], v198 offset:36864
	ds_read_b128 v[180:183], v198 offset:37888
	ds_read_b128 v[200:203], v198 offset:38912
	ds_read_b128 v[204:207], v198 offset:39936
	global_load_lds_dwordx4 v[208:209], off
	v_lshl_add_u64 v[208:209], s[28:29], 0, v[136:137]
	s_mov_b32 m0, s41
	s_nop 0
	global_load_lds_dwordx4 v[208:209], off
	s_waitcnt lgkmcnt(8)
	s_barrier
	s_waitcnt lgkmcnt(0)
	s_setprio 1
	s_waitcnt lgkmcnt(0)
	v_mfma_f32_16x16x32_bf16 v[126:129], v[130:133], v[160:163], v[126:129]
	v_mfma_f32_16x16x32_bf16 v[122:125], v[152:155], v[160:163], v[122:125]
	v_mfma_f32_16x16x32_bf16 v[118:121], v[130:133], v[168:171], v[118:121]
	v_mfma_f32_16x16x32_bf16 v[106:109], v[152:155], v[168:171], v[106:109]
	v_mfma_f32_16x16x32_bf16 v[98:101], v[130:133], v[176:179], v[98:101]
	v_mfma_f32_16x16x32_bf16 v[90:93], v[152:155], v[176:179], v[90:93]
	v_mfma_f32_16x16x32_bf16 v[82:85], v[130:133], v[200:203], v[82:85]
	v_mfma_f32_16x16x32_bf16 v[74:77], v[152:155], v[200:203], v[74:77]
	v_mfma_f32_16x16x32_bf16 v[126:129], v[148:151], v[164:167], v[126:129]
	v_mfma_f32_16x16x32_bf16 v[122:125], v[156:159], v[164:167], v[122:125]
	v_mfma_f32_16x16x32_bf16 v[118:121], v[148:151], v[172:175], v[118:121]
	v_mfma_f32_16x16x32_bf16 v[106:109], v[156:159], v[172:175], v[106:109]
	v_mfma_f32_16x16x32_bf16 v[98:101], v[148:151], v[180:183], v[98:101]
	v_mfma_f32_16x16x32_bf16 v[90:93], v[156:159], v[180:183], v[90:93]
	v_mfma_f32_16x16x32_bf16 v[82:85], v[148:151], v[204:207], v[82:85]
	v_mfma_f32_16x16x32_bf16 v[74:77], v[156:159], v[204:207], v[74:77]
	s_setprio 0
	s_barrier
	s_add_i32 s23, 0, 0x1c000
	s_add_i32 s21, s21, s31
	v_add_u32_e32 v16, s23, v186
	v_lshl_add_u64 v[184:185], v[184:185], 0, s[16:17]
	s_mov_b32 m0, s21
	ds_read_b128 v[208:211], v16
	ds_read_b128 v[212:215], v16 offset:1024
	ds_read_b128 v[216:219], v16 offset:2048
	ds_read_b128 v[220:223], v16 offset:3072
	global_load_lds_dwordx4 v[184:185], off
	v_lshl_add_u64 v[184:185], v[224:225], 0, s[16:17]
	s_add_i32 m0, s21, 0x2000
	s_nop 0
	global_load_lds_dwordx4 v[184:185], off
	s_barrier
	s_waitcnt lgkmcnt(0)
	s_setprio 1
	s_waitcnt lgkmcnt(0)
	v_mfma_f32_16x16x32_bf16 v[114:117], v[208:211], v[160:163], v[114:117]
	v_mfma_f32_16x16x32_bf16 v[110:113], v[216:219], v[160:163], v[110:113]
	v_mfma_f32_16x16x32_bf16 v[102:105], v[208:211], v[168:171], v[102:105]
	v_mfma_f32_16x16x32_bf16 v[94:97], v[216:219], v[168:171], v[94:97]
	v_mfma_f32_16x16x32_bf16 v[86:89], v[208:211], v[176:179], v[86:89]
	v_mfma_f32_16x16x32_bf16 v[78:81], v[216:219], v[176:179], v[78:81]
	v_mfma_f32_16x16x32_bf16 v[70:73], v[208:211], v[200:203], v[70:73]
	v_mfma_f32_16x16x32_bf16 v[66:69], v[216:219], v[200:203], v[66:69]
	v_mfma_f32_16x16x32_bf16 v[114:117], v[212:215], v[164:167], v[114:117]
	v_mfma_f32_16x16x32_bf16 v[110:113], v[220:223], v[164:167], v[110:113]
	v_mfma_f32_16x16x32_bf16 v[102:105], v[212:215], v[172:175], v[102:105]
	v_mfma_f32_16x16x32_bf16 v[94:97], v[220:223], v[172:175], v[94:97]
	v_mfma_f32_16x16x32_bf16 v[86:89], v[212:215], v[180:183], v[86:89]
	v_mfma_f32_16x16x32_bf16 v[78:81], v[220:223], v[180:183], v[78:81]
	v_mfma_f32_16x16x32_bf16 v[70:73], v[212:215], v[204:207], v[70:73]
	v_mfma_f32_16x16x32_bf16 v[66:69], v[220:223], v[204:207], v[66:69]
	s_setprio 0
	s_mov_b32 m0, s43
	v_lshl_add_u64 v[184:185], v[226:227], 0, s[16:17]
	s_barrier
	ds_read_b128 v[160:163], v198 offset:49152
	ds_read_b128 v[164:167], v198 offset:50176
	ds_read_b128 v[168:171], v198 offset:51200
	ds_read_b128 v[172:175], v198 offset:52224
	ds_read_b128 v[176:179], v198 offset:53248
	ds_read_b128 v[180:183], v198 offset:54272
	ds_read_b128 v[200:203], v198 offset:55296
	ds_read_b128 v[204:207], v198 offset:56320
	global_load_lds_dwordx4 v[184:185], off
	v_lshl_add_u64 v[184:185], v[228:229], 0, s[16:17]
	s_mov_b32 m0, s44
	s_nop 0
	global_load_lds_dwordx4 v[184:185], off
	s_barrier
; #define PG8_STAGE(bufoff, gbase, voff) do { _Pragma("unroll") for (int _i = 0; _i < 2; ++_i) \
;     __builtin_amdgcn_global_load_lds((const unsigned*)((const char*)(gbase) + (voff)[_i]), (LAS unsigned*)(lds + (bufoff) + ldsw + _i * 8192), 16, 0, 0); } while (0)
; #define PG8_MMA(ai, bj, At, Bt) do { __builtin_amdgcn_s_setprio(1); _Pragma("unroll") for (int m = 0; m < 4; ++m) _Pragma("unroll") for (int n = 0; n < 2; ++n) _Pragma("unroll") for (int k = 0; k < 2; ++k) \
;     acc[ai][bj][m][n] = __builtin_amdgcn_mfma_f32_16x16x32_bf16(Bt[n][k], At[m][k], acc[ai][bj][m][n], 0, 0, 0); __builtin_amdgcn_s_setprio(0); } while (0)
; #define PG8_WAIT_V(n) asm volatile("s_waitcnt vmcnt(" #n ")" ::: "memory")
; #define PG8_WAIT_L(n) asm volatile("s_waitcnt lgkmcnt(" #n ")" ::: "memory")
; #define PG8_BAR __builtin_amdgcn_s_barrier()
; #define PG8_SCHED __builtin_amdgcn_sched_barrier(0)
; template <class Epi>
; __device__ __forceinline__ void gemm_phase(LAS unsigned char* lds, const Gemm g, const StaticOrder& S, const Epi& E) {
;     ...
;       PG8_BAR; PG8_WAIT_L(0); PG8_MMA(1, 0, At, B0); PG8_BAR; PG8_SCHED;
;       PG8_STAGE(PG8_SB(1, 1), b3 + hstepB, voffB);
;       PG8_WAIT_V(6); PG8_BAR; PG8_MMA(1, 1, At, B1); PG8_BAR;
;   __device__ __forceinline__ void operator()(const f32x4 (&acc)[2][2][4][2], const Unit& u, int wr, int wc, int fr, int fq) const {
;     ...
;       float* pbase = part + (size_t)(u.kt0 / u.nt) * MS * 1024;
; #pragma unroll
;       for (int ai = 0; ai < 2; ++ai)
; #pragma unroll
;         for (int m = 0; m < 4; ++m) {
;           float* orow = pbase + (size_t)(u.pm * 256 + ai * 128 + wr * 64 + m * 16 + fr - MP) * 1024;
; #pragma unroll
;           for (int bj = 0; bj < 2; ++bj)
; #pragma unroll
;             for (int n = 0; n < 2; ++n) *(f32x4*)(orow + u.pn * 256 + bj * 128 + wc * 32 + 16 * n + 4 * fq) = acc[ai][bj][m][n];
	s_waitcnt lgkmcnt(0)
	s_setprio 1
	s_waitcnt lgkmcnt(0)
	v_mfma_f32_16x16x32_bf16 v[62:65], v[130:133], v[160:163], v[62:65]
	v_mfma_f32_16x16x32_bf16 v[58:61], v[152:155], v[160:163], v[58:61]
	v_mfma_f32_16x16x32_bf16 v[50:53], v[130:133], v[168:171], v[50:53]
	v_mfma_f32_16x16x32_bf16 v[42:45], v[152:155], v[168:171], v[42:45]
	v_mfma_f32_16x16x32_bf16 v[34:37], v[130:133], v[176:179], v[34:37]
	v_mfma_f32_16x16x32_bf16 v[26:29], v[152:155], v[176:179], v[26:29]
	v_mfma_f32_16x16x32_bf16 v[18:21], v[130:133], v[200:203], v[18:21]
	v_mfma_f32_16x16x32_bf16 v[8:11], v[152:155], v[200:203], v[8:11]
	v_mfma_f32_16x16x32_bf16 v[62:65], v[148:151], v[164:167], v[62:65]
	v_mfma_f32_16x16x32_bf16 v[58:61], v[156:159], v[164:167], v[58:61]
	v_mfma_f32_16x16x32_bf16 v[50:53], v[148:151], v[172:175], v[50:53]
	v_mfma_f32_16x16x32_bf16 v[42:45], v[156:159], v[172:175], v[42:45]
	v_mfma_f32_16x16x32_bf16 v[34:37], v[148:151], v[180:183], v[34:37]
	v_mfma_f32_16x16x32_bf16 v[26:29], v[156:159], v[180:183], v[26:29]
	v_mfma_f32_16x16x32_bf16 v[18:21], v[148:151], v[204:207], v[18:21]
	v_mfma_f32_16x16x32_bf16 v[8:11], v[156:159], v[204:207], v[8:11]
	s_setprio 0
	s_barrier
	s_add_u32 s26, s26, 0x40080
	s_addc_u32 s27, s27, 0
	s_add_i32 s21, s23, s31
	v_lshl_add_u64 v[130:131], s[26:27], 0, v[134:135]
	s_mov_b32 m0, s21
	s_nop 0
	global_load_lds_dwordx4 v[130:131], off
	v_lshl_add_u64 v[130:131], s[26:27], 0, v[136:137]
	s_add_i32 m0, s21, 0x2000
	s_nop 0
	global_load_lds_dwordx4 v[130:131], off
	s_waitcnt vmcnt(6)
	s_barrier
	s_setprio 1
	v_mfma_f32_16x16x32_bf16 v[54:57], v[208:211], v[160:163], v[54:57]
	v_mfma_f32_16x16x32_bf16 v[46:49], v[216:219], v[160:163], v[46:49]
	v_mfma_f32_16x16x32_bf16 v[38:41], v[208:211], v[168:171], v[38:41]
	v_mfma_f32_16x16x32_bf16 v[30:33], v[216:219], v[168:171], v[30:33]
	v_mfma_f32_16x16x32_bf16 v[22:25], v[208:211], v[176:179], v[22:25]
	v_mfma_f32_16x16x32_bf16 v[12:15], v[216:219], v[176:179], v[12:15]
	v_mfma_f32_16x16x32_bf16 v[4:7], v[208:211], v[200:203], v[4:7]
	v_mfma_f32_16x16x32_bf16 v[0:3], v[216:219], v[200:203], v[0:3]
	v_mfma_f32_16x16x32_bf16 v[54:57], v[212:215], v[164:167], v[54:57]
	v_mfma_f32_16x16x32_bf16 v[46:49], v[220:223], v[164:167], v[46:49]
	v_mfma_f32_16x16x32_bf16 v[38:41], v[212:215], v[172:175], v[38:41]
	v_mfma_f32_16x16x32_bf16 v[30:33], v[220:223], v[172:175], v[30:33]
	v_mfma_f32_16x16x32_bf16 v[22:25], v[212:215], v[180:183], v[22:25]
	v_mfma_f32_16x16x32_bf16 v[12:15], v[220:223], v[180:183], v[12:15]
	v_mfma_f32_16x16x32_bf16 v[4:7], v[212:215], v[204:207], v[4:7]
	v_mfma_f32_16x16x32_bf16 v[0:3], v[220:223], v[204:207], v[0:3]
	s_setprio 0
	s_add_i32 s21, s11, 2
	s_add_u32 s24, s24, 0x100
	s_addc_u32 s25, s25, 0
	s_add_u32 s7, s7, 0x100
	s_addc_u32 s9, s9, 0
	s_cmp_ge_i32 s11, s50
	s_mov_b32 s11, s21
	s_barrier
	s_cbranch_scc0 .LBB0_3657
	s_nop 7
	v_and_b32_e32 v200, 3, v252
	v_lshlrev_b32_e32 v200, 4, v200
	v_and_b32_e32 v201, 12, v252
	v_bfe_u32 v202, v252, 4, 2
	v_or3_b32 v200, v200, v201, v202
	v_lshlrev_b32_e32 v200, 2, v200
	ds_bpermute_b32 v0, v200, v0
	ds_bpermute_b32 v1, v200, v1
	ds_bpermute_b32 v2, v200, v2
	ds_bpermute_b32 v3, v200, v3
	ds_bpermute_b32 v4, v200, v4
	ds_bpermute_b32 v5, v200, v5
	ds_bpermute_b32 v6, v200, v6
	ds_bpermute_b32 v7, v200, v7
	ds_bpermute_b32 v8, v200, v8
	ds_bpermute_b32 v9, v200, v9
	ds_bpermute_b32 v10, v200, v10
	ds_bpermute_b32 v11, v200, v11
	s_waitcnt lgkmcnt(0)
	ds_bpermute_b32 v12, v200, v12
	ds_bpermute_b32 v13, v200, v13
	ds_bpermute_b32 v14, v200, v14
	ds_bpermute_b32 v15, v200, v15
	ds_bpermute_b32 v18, v200, v18
	ds_bpermute_b32 v19, v200, v19
	ds_bpermute_b32 v20, v200, v20
	ds_bpermute_b32 v21, v200, v21
	ds_bpermute_b32 v22, v200, v22
	ds_bpermute_b32 v23, v200, v23
	ds_bpermute_b32 v24, v200, v24
	ds_bpermute_b32 v25, v200, v25
	s_waitcnt lgkmcnt(0)
	ds_bpermute_b32 v26, v200, v26
	ds_bpermute_b32 v27, v200, v27
	ds_bpermute_b32 v28, v200, v28
	ds_bpermute_b32 v29, v200, v29
	ds_bpermute_b32 v30, v200, v30
	ds_bpermute_b32 v31, v200, v31
	ds_bpermute_b32 v32, v200, v32
	ds_bpermute_b32 v33, v200, v33
	ds_bpermute_b32 v34, v200, v34
	ds_bpermute_b32 v35, v200, v35
	ds_bpermute_b32 v36, v200, v36
	ds_bpermute_b32 v37, v200, v37
	s_waitcnt lgkmcnt(0)
	ds_bpermute_b32 v38, v200, v38
	ds_bpermute_b32 v39, v200, v39
	ds_bpermute_b32 v40, v200, v40
	ds_bpermute_b32 v41, v200, v41
	ds_bpermute_b32 v42, v200, v42
	ds_bpermute_b32 v43, v200, v43
	ds_bpermute_b32 v44, v200, v44
	ds_bpermute_b32 v45, v200, v45
	ds_bpermute_b32 v46, v200, v46
	ds_bpermute_b32 v47, v200, v47
	ds_bpermute_b32 v48, v200, v48
	ds_bpermute_b32 v49, v200, v49
	s_waitcnt lgkmcnt(0)
	ds_bpermute_b32 v50, v200, v50
	ds_bpermute_b32 v51, v200, v51
	ds_bpermute_b32 v52, v200, v52
	ds_bpermute_b32 v53, v200, v53
	ds_bpermute_b32 v54, v200, v54
	ds_bpermute_b32 v55, v200, v55
	ds_bpermute_b32 v56, v200, v56
	ds_bpermute_b32 v57, v200, v57
	ds_bpermute_b32 v58, v200, v58
	ds_bpermute_b32 v59, v200, v59
	ds_bpermute_b32 v60, v200, v60
	ds_bpermute_b32 v61, v200, v61
	s_waitcnt lgkmcnt(0)
	ds_bpermute_b32 v62, v200, v62
	ds_bpermute_b32 v63, v200, v63
	ds_bpermute_b32 v64, v200, v64
	ds_bpermute_b32 v65, v200, v65
	ds_bpermute_b32 v66, v200, v66
	ds_bpermute_b32 v67, v200, v67
	ds_bpermute_b32 v68, v200, v68
	ds_bpermute_b32 v69, v200, v69
	ds_bpermute_b32 v70, v200, v70
	ds_bpermute_b32 v71, v200, v71
	ds_bpermute_b32 v72, v200, v72
	ds_bpermute_b32 v73, v200, v73
	s_waitcnt lgkmcnt(0)
;   __device__ __forceinline__ void operator()(const f32x4 (&acc)[2][2][4][2], const Unit& u, int wr, int wc, int fr, int fq) const {
;     if (u.split) {
;       float* pbase = part + (size_t)(u.kt0 / u.nt) * MS * 1024;
; #pragma unroll
;       for (int ai = 0; ai < 2; ++ai)
; #pragma unroll
;         for (int m = 0; m < 4; ++m) {
;           float* orow = pbase + (size_t)(u.pm * 256 + ai * 128 + wr * 64 + m * 16 + fr - MP) * 1024;
; #pragma unroll
;           for (int bj = 0; bj < 2; ++bj)
; #pragma unroll
;             for (int n = 0; n < 2; ++n) *(f32x4*)(orow + u.pn * 256 + bj * 128 + wc * 32 + 16 * n + 4 * fq) = acc[ai][bj][m][n];
;         }
;       return;
	ds_bpermute_b32 v74, v200, v74
	ds_bpermute_b32 v75, v200, v75
	ds_bpermute_b32 v76, v200, v76
	ds_bpermute_b32 v77, v200, v77
	ds_bpermute_b32 v78, v200, v78
	ds_bpermute_b32 v79, v200, v79
	ds_bpermute_b32 v80, v200, v80
	ds_bpermute_b32 v81, v200, v81
	ds_bpermute_b32 v82, v200, v82
	ds_bpermute_b32 v83, v200, v83
	ds_bpermute_b32 v84, v200, v84
	ds_bpermute_b32 v85, v200, v85
	s_waitcnt lgkmcnt(0)
	ds_bpermute_b32 v86, v200, v86
	ds_bpermute_b32 v87, v200, v87
	ds_bpermute_b32 v88, v200, v88
	ds_bpermute_b32 v89, v200, v89
	ds_bpermute_b32 v90, v200, v90
	ds_bpermute_b32 v91, v200, v91
	ds_bpermute_b32 v92, v200, v92
	ds_bpermute_b32 v93, v200, v93
	ds_bpermute_b32 v94, v200, v94
	ds_bpermute_b32 v95, v200, v95
	ds_bpermute_b32 v96, v200, v96
	ds_bpermute_b32 v97, v200, v97
	s_waitcnt lgkmcnt(0)
	ds_bpermute_b32 v98, v200, v98
	ds_bpermute_b32 v99, v200, v99
	ds_bpermute_b32 v100, v200, v100
	ds_bpermute_b32 v101, v200, v101
	ds_bpermute_b32 v102, v200, v102
	ds_bpermute_b32 v103, v200, v103
	ds_bpermute_b32 v104, v200, v104
	ds_bpermute_b32 v105, v200, v105
	ds_bpermute_b32 v106, v200, v106
	ds_bpermute_b32 v107, v200, v107
	ds_bpermute_b32 v108, v200, v108
	ds_bpermute_b32 v109, v200, v109
	s_waitcnt lgkmcnt(0)
	ds_bpermute_b32 v110, v200, v110
	ds_bpermute_b32 v111, v200, v111
	ds_bpermute_b32 v112, v200, v112
	ds_bpermute_b32 v113, v200, v113
	ds_bpermute_b32 v114, v200, v114
	ds_bpermute_b32 v115, v200, v115
	ds_bpermute_b32 v116, v200, v116
	ds_bpermute_b32 v117, v200, v117
	ds_bpermute_b32 v118, v200, v118
	ds_bpermute_b32 v119, v200, v119
	ds_bpermute_b32 v120, v200, v120
	ds_bpermute_b32 v121, v200, v121
	s_waitcnt lgkmcnt(0)
	ds_bpermute_b32 v122, v200, v122
	ds_bpermute_b32 v123, v200, v123
	ds_bpermute_b32 v124, v200, v124
	ds_bpermute_b32 v125, v200, v125
	ds_bpermute_b32 v126, v200, v126
	ds_bpermute_b32 v127, v200, v127
	ds_bpermute_b32 v128, v200, v128
	ds_bpermute_b32 v129, v200, v129
	s_waitcnt lgkmcnt(0)
	s_cmp_eq_u32 s52, 0
	v_lshlrev_b32_e32 v16, 2, v138
	s_cbranch_scc1 .LBB0_3660
	s_abs_i32 s7, s50
	v_cvt_f32_u32_e32 v130, s7
	s_sub_i32 s21, 0, s7
	s_abs_i32 s11, s51
	s_xor_b32 s9, s51, s50
	v_rcp_iflag_f32_e32 v130, v130
	s_ashr_i32 s9, s9, 31
	v_mul_f32_e32 v130, 0x4f7ffffe, v130
	v_cvt_u32_f32_e32 v130, v130
	s_nop 0
	v_readfirstlane_b32 s23, v130
	s_mul_i32 s21, s21, s23
	s_mul_hi_u32 s21, s23, s21
	s_add_i32 s23, s23, s21
	s_mul_hi_u32 s21, s11, s23
	s_mul_i32 s23, s21, s7
	s_sub_i32 s11, s11, s23
	s_add_i32 s24, s21, 1
	s_sub_i32 s23, s11, s7
	s_cmp_ge_u32 s11, s7
	s_cselect_b32 s21, s24, s21
	s_cselect_b32 s11, s23, s11
	s_add_i32 s23, s21, 1
	s_cmp_ge_u32 s11, s7
	s_cselect_b32 s7, s23, s21
	s_xor_b32 s7, s7, s9
	s_sub_i32 s24, s7, s9
	s_ashr_i32 s25, s24, 31
	s_lshl_b64 s[24:25], s[24:25], 21
	s_add_u32 s24, s45, s24
	s_addc_u32 s25, s46, s25
	s_lshl_b32 s7, s22, 8
	v_add_u32_e32 v130, s7, v187
	s_lshl_b32 s26, s20, 8
	v_ashrrev_i32_e32 v131, 31, v130
	s_ashr_i32 s27, s26, 31
	v_lshlrev_b64 v[132:133], 12, v[130:131]
	v_lshl_add_u64 v[132:133], s[24:25], 0, v[132:133]
	s_lshl_b64 s[26:27], s[26:27], 2
	v_lshl_add_u64 v[132:133], v[132:133], 0, s[26:27]
	v_lshl_add_u64 v[132:133], v[132:133], 0, v[16:17]
	global_store_dwordx4 v[132:133], v[126:129], off
	global_store_dwordx4 v[132:133], v[122:125], off offset:64
	global_store_dwordx4 v[132:133], v[114:117], off offset:512
	global_store_dwordx4 v[132:133], v[110:113], off offset:576
	v_add_u32_e32 v132, s7, v188
	v_ashrrev_i32_e32 v133, 31, v132
	v_lshlrev_b64 v[132:133], 12, v[132:133]
	v_lshl_add_u64 v[132:133], s[24:25], 0, v[132:133]
	v_lshl_add_u64 v[132:133], v[132:133], 0, s[26:27]
	v_lshl_add_u64 v[132:133], v[132:133], 0, v[16:17]
	global_store_dwordx4 v[132:133], v[118:121], off
	global_store_dwordx4 v[132:133], v[106:109], off offset:64
	global_store_dwordx4 v[132:133], v[102:105], off offset:512
	global_store_dwordx4 v[132:133], v[94:97], off offset:576
	v_add_u32_e32 v132, s7, v189
	v_ashrrev_i32_e32 v133, 31, v132
	v_lshlrev_b64 v[132:133], 12, v[132:133]
	v_lshl_add_u64 v[132:133], s[24:25], 0, v[132:133]
	v_lshl_add_u64 v[132:133], v[132:133], 0, s[26:27]
	v_lshl_add_u64 v[132:133], v[132:133], 0, v[16:17]
	global_store_dwordx4 v[132:133], v[98:101], off
	global_store_dwordx4 v[132:133], v[90:93], off offset:64
	global_store_dwordx4 v[132:133], v[86:89], off offset:512
	global_store_dwordx4 v[132:133], v[78:81], off offset:576
	v_add_u32_e32 v132, s7, v190
	v_ashrrev_i32_e32 v133, 31, v132
	v_lshlrev_b64 v[132:133], 12, v[132:133]
	v_lshl_add_u64 v[132:133], s[24:25], 0, v[132:133]
	v_lshl_add_u64 v[132:133], v[132:133], 0, s[26:27]
	v_lshl_add_u64 v[132:133], v[132:133], 0, v[16:17]
	global_store_dwordx4 v[132:133], v[82:85], off
	global_store_dwordx4 v[132:133], v[74:77], off offset:64
	global_store_dwordx4 v[132:133], v[70:73], off offset:512
	global_store_dwordx4 v[132:133], v[66:69], off offset:576
	v_add_u32_e32 v132, 0x80, v130
	v_ashrrev_i32_e32 v133, 31, v132
	v_lshlrev_b64 v[132:133], 12, v[132:133]
	v_lshl_add_u64 v[132:133], s[24:25], 0, v[132:133]
	v_lshl_add_u64 v[132:133], v[132:133], 0, s[26:27]
	v_lshl_add_u64 v[132:133], v[132:133], 0, v[16:17]
	global_store_dwordx4 v[132:133], v[62:65], off
	global_store_dwordx4 v[132:133], v[58:61], off offset:64
	global_store_dwordx4 v[132:133], v[54:57], off offset:512
	global_store_dwordx4 v[132:133], v[46:49], off offset:576
	v_add_u32_e32 v132, 0x90, v130
	v_ashrrev_i32_e32 v133, 31, v132
	v_lshlrev_b64 v[132:133], 12, v[132:133]
	v_lshl_add_u64 v[132:133], s[24:25], 0, v[132:133]
	v_lshl_add_u64 v[132:133], v[132:133], 0, s[26:27]
	v_lshl_add_u64 v[132:133], v[132:133], 0, v[16:17]
	global_store_dwordx4 v[132:133], v[50:53], off
	global_store_dwordx4 v[132:133], v[42:45], off offset:64
	global_store_dwordx4 v[132:133], v[38:41], off offset:512
	global_store_dwordx4 v[132:133], v[30:33], off offset:576
	v_add_u32_e32 v132, 0xa0, v130
	v_ashrrev_i32_e32 v133, 31, v132
	v_add_u32_e32 v130, 0xb0, v130
	v_lshlrev_b64 v[132:133], 12, v[132:133]
	v_ashrrev_i32_e32 v131, 31, v130
	v_lshl_add_u64 v[132:133], s[24:25], 0, v[132:133]
	v_lshlrev_b64 v[130:131], 12, v[130:131]
	v_lshl_add_u64 v[132:133], v[132:133], 0, s[26:27]
	v_lshl_add_u64 v[130:131], s[24:25], 0, v[130:131]
	v_lshl_add_u64 v[132:133], v[132:133], 0, v[16:17]
	v_lshl_add_u64 v[130:131], v[130:131], 0, s[26:27]
	s_mov_b64 s[24:25], 0x240
	global_store_dwordx4 v[132:133], v[34:37], off
	global_store_dwordx4 v[132:133], v[26:29], off offset:64
	global_store_dwordx4 v[132:133], v[22:25], off offset:512
	global_store_dwordx4 v[132:133], v[12:15], off offset:576
	v_lshl_add_u64 v[132:133], v[130:131], 0, v[16:17]
	v_lshl_add_u64 v[170:171], v[130:131], 0, s[24:25]
	global_store_dwordx4 v[132:133], v[18:21], off
	global_store_dwordx4 v[132:133], v[8:11], off offset:64
	global_store_dwordx4 v[132:133], v[4:7], off offset:512
	s_cbranch_execnz .LBB0_3642
	s_branch .LBB0_3661
